# as v53 plus: redundant loop-end workgroup barrier of the UP GEMM tile loop removed (next tile issues no LDS-DMA into the staging region before its own first barrier)
# speedup vs baseline: 1.0017x; 1.0006x over previous
; template <int MODE>
; DI void gemm_tile(const Params& p, const bf16_t* __restrict__ A, const bf16_t* __restrict__ Bt, int K, int brow, int bcol, int mp, int nt, bool vt, char* smem) {
;     ...
;       for (int m = 0; m < 4; ++m)
; #pragma unroll
;         for (int n = 0; n < 2; ++n) *(f32x4*)(st + (wc * 32 + n * 16 + fr) * 132 + wr * 64 + m * 16 + fq * 4) = acc[ai][bj][m][n];
;       __syncthreads();
; #pragma unroll 1
;       for (int pg = 0; pg < 2; ++pg) {
;       u32x2 xo[4];
;       if (RESID) {
; #pragma unroll
;         for (int pq = 0; pq < 4; ++pq) xo[pq] = xnx[pq];
;         const int q = ai * 2 + bj, nq = pg ? q + 1 : q, npg = pg ^ 1;
;         if (nq < 4) {
;           const int nai = nq >> 1, nbj = nq & 1;
; #pragma unroll
;           for (int pq = 0; pq < 4; ++pq)
;             xnx[pq] = *(const u32x2*)((const bf16_t*)(p.ws + OFF_XB) + (size_t)(m0 + nbj * 128 + (npg * 4 + pq) * 16 + (tid >> 5)) * DM + n0 + nai * 128 + (tid & 31) * 4);
;         }
;       }
; #pragma unroll
;       for (int pq = 0; pq < 4; ++pq) {
;         const int pass = pg * 4 + pq;
;         const int y = pass * 16 + (tid >> 5), x4 = (tid & 31) * 4;
;         const f32x4 v = *(const f32x4*)(st + y * 132 + x4);
;         if (MODE == MODE_PROJ) {
;           if (vt) {
;             const int vrow = (nt - 8) * 256 + bj * 128 + y, tk = m0 + ai * 128 + x4, b = tk >> 11, sq = tk & 2047;
;             const f32x4 rr = *(const f32x4*)(rsl + ai * 128 + x4);
;             u32x2 o = {pk2(v[0] * rr[0], v[1] * rr[1]), pk2(v[2] * rr[2], v[3] * rr[3])};
;             *(u32x2*)((bf16_t*)(p.ws + OFF_VT) + ((size_t)(b * VROWS + vrow)) * SEQ + sq) = o;
;           } else {
;             const int tok = m0 + bj * 128 + y, col = n0 + ai * 128 + x4;
;             const float rs = rsl[bj * 128 + y];
;             if (col < QKW) {
;               u32x2 o = {pk2(v[0] * rs, v[1] * rs), pk2(v[2] * rs, v[3] * rs)};
;               *(u32x2*)((bf16_t*)(p.ws + OFF_QK) + (size_t)tok * QKW + col) = o;
;             } else if (col < QKW + 16) {
;               f32x4 o = {v[0] * rs, v[1] * rs, v[2] * rs, v[3] * rs};
;               *(f32x4*)((float*)(p.ws + OFF_GATE) + (size_t)tok * 16 + (col - QKW)) = o;
;             }
;           }
;         } else if (MODE == MODE_UP) {
;           const int tok = m0 + bj * 128 + y, col = n0 + ai * 128 + x4;
;           const float rs = rsl[bj * 128 + y];
.Lup_noearly:
	s_waitcnt lgkmcnt(0)
	s_barrier
	v_mul_f32_e32 v98, v98, v144
	v_mul_f32_e32 v99, v99, v144
	v_mul_f32_e32 v100, v100, v144
	v_mul_f32_e32 v101, v101, v144
	v_max_f32_e32 v98, 0, v98
	v_max_f32_e32 v99, 0, v99
	v_max_f32_e32 v100, 0, v100
	v_max_f32_e32 v101, 0, v101
	v_pk_mul_f32 v[98:99], v[98:99], v[98:99]
	v_pk_mul_f32 v[100:101], v[100:101], v[100:101]
	v_cvt_pk_bf16_f32 v98, v98, v99
	v_cvt_pk_bf16_f32 v99, v100, v101
	ds_write_b64 v134, v[98:99]
	v_mul_f32_e32 v102, v102, v145
	v_mul_f32_e32 v103, v103, v145
	v_mul_f32_e32 v104, v104, v145
	v_mul_f32_e32 v105, v105, v145
	v_max_f32_e32 v102, 0, v102
	v_max_f32_e32 v103, 0, v103
	v_max_f32_e32 v104, 0, v104
	v_max_f32_e32 v105, 0, v105
	v_pk_mul_f32 v[102:103], v[102:103], v[102:103]
	v_pk_mul_f32 v[104:105], v[104:105], v[104:105]
	v_cvt_pk_bf16_f32 v102, v102, v103
	v_cvt_pk_bf16_f32 v103, v104, v105
	ds_write_b64 v134, v[102:103] offset:4224
	v_mul_f32_e32 v106, v106, v144
	v_mul_f32_e32 v107, v107, v144
	v_mul_f32_e32 v108, v108, v144
	v_mul_f32_e32 v109, v109, v144
	v_max_f32_e32 v106, 0, v106
	v_max_f32_e32 v107, 0, v107
	v_max_f32_e32 v108, 0, v108
	v_max_f32_e32 v109, 0, v109
	v_pk_mul_f32 v[106:107], v[106:107], v[106:107]
	v_pk_mul_f32 v[108:109], v[108:109], v[108:109]
	v_cvt_pk_bf16_f32 v106, v106, v107
	v_cvt_pk_bf16_f32 v107, v108, v109
	ds_write_b64 v134, v[106:107] offset:32
	v_mul_f32_e32 v110, v110, v145
	v_mul_f32_e32 v111, v111, v145
	v_mul_f32_e32 v112, v112, v145
	v_mul_f32_e32 v113, v113, v145
	v_max_f32_e32 v110, 0, v110
	v_max_f32_e32 v111, 0, v111
	v_max_f32_e32 v112, 0, v112
	v_max_f32_e32 v113, 0, v113
	v_pk_mul_f32 v[110:111], v[110:111], v[110:111]
	v_pk_mul_f32 v[112:113], v[112:113], v[112:113]
	v_cvt_pk_bf16_f32 v110, v110, v111
	v_cvt_pk_bf16_f32 v111, v112, v113
	ds_write_b64 v134, v[110:111] offset:4256
	v_mul_f32_e32 v114, v114, v144
	v_mul_f32_e32 v115, v115, v144
	v_mul_f32_e32 v116, v116, v144
	v_mul_f32_e32 v117, v117, v144
	v_max_f32_e32 v114, 0, v114
	v_max_f32_e32 v115, 0, v115
	v_max_f32_e32 v116, 0, v116
	v_max_f32_e32 v117, 0, v117
	v_pk_mul_f32 v[114:115], v[114:115], v[114:115]
	v_pk_mul_f32 v[116:117], v[116:117], v[116:117]
	v_cvt_pk_bf16_f32 v114, v114, v115
	v_cvt_pk_bf16_f32 v115, v116, v117
	ds_write_b64 v134, v[114:115] offset:64
	v_mul_f32_e32 v118, v118, v145
	v_mul_f32_e32 v119, v119, v145
	v_mul_f32_e32 v120, v120, v145
	v_mul_f32_e32 v121, v121, v145
	v_max_f32_e32 v118, 0, v118
	v_max_f32_e32 v119, 0, v119
	v_max_f32_e32 v120, 0, v120
	v_max_f32_e32 v121, 0, v121
	v_pk_mul_f32 v[118:119], v[118:119], v[118:119]
	v_pk_mul_f32 v[120:121], v[120:121], v[120:121]
	v_cvt_pk_bf16_f32 v118, v118, v119
	v_cvt_pk_bf16_f32 v119, v120, v121
	ds_write_b64 v134, v[118:119] offset:4288
	v_mul_f32_e32 v122, v122, v144
	v_mul_f32_e32 v123, v123, v144
	v_mul_f32_e32 v124, v124, v144
	v_mul_f32_e32 v125, v125, v144
	v_max_f32_e32 v122, 0, v122
	v_max_f32_e32 v123, 0, v123
	v_max_f32_e32 v124, 0, v124
	v_max_f32_e32 v125, 0, v125
	v_pk_mul_f32 v[122:123], v[122:123], v[122:123]
	v_pk_mul_f32 v[124:125], v[124:125], v[124:125]
	v_cvt_pk_bf16_f32 v122, v122, v123
	v_cvt_pk_bf16_f32 v123, v124, v125
	ds_write_b64 v134, v[122:123] offset:96
	v_mul_f32_e32 v126, v126, v145
	v_mul_f32_e32 v127, v127, v145
	v_mul_f32_e32 v128, v128, v145
	v_mul_f32_e32 v129, v129, v145
	v_max_f32_e32 v126, 0, v126
	v_max_f32_e32 v127, 0, v127
	v_max_f32_e32 v128, 0, v128
	v_max_f32_e32 v129, 0, v129
	v_pk_mul_f32 v[126:127], v[126:127], v[126:127]
	v_pk_mul_f32 v[128:129], v[128:129], v[128:129]
	v_cvt_pk_bf16_f32 v126, v126, v127
	v_cvt_pk_bf16_f32 v127, v128, v129
	ds_write_b64 v134, v[126:127] offset:4320
	s_waitcnt lgkmcnt(0)
	s_barrier
	ds_read_b64 v[114:115], v135
	ds_read_b64 v[116:117], v135 offset:4224
	ds_read_b64 v[118:119], v135 offset:8448
	ds_read_b64 v[120:121], v135 offset:12672
	ds_read_b64 v[122:123], v135 offset:16896
	ds_read_b64 v[124:125], v135 offset:21120
	ds_read_b64 v[126:127], v135 offset:25344
	ds_read_b64 v[128:129], v135 offset:29568
	s_waitcnt lgkmcnt(7)
	global_store_dwordx2 v132, v[114:115], s[6:7]
	s_waitcnt lgkmcnt(6)
	v_add_u32_e32 v136, 0x20000, v132
	global_store_dwordx2 v136, v[116:117], s[6:7]
	s_waitcnt lgkmcnt(5)
	v_add_u32_e32 v136, 0x40000, v132
	global_store_dwordx2 v136, v[118:119], s[6:7]
	s_waitcnt lgkmcnt(4)
	v_add_u32_e32 v136, 0x60000, v132
	global_store_dwordx2 v136, v[120:121], s[6:7]
	s_waitcnt lgkmcnt(3)
	v_add_u32_e32 v136, 0x80000, v132
	global_store_dwordx2 v136, v[122:123], s[6:7]
	s_waitcnt lgkmcnt(2)
	v_add_u32_e32 v136, 0xa0000, v132
	global_store_dwordx2 v136, v[124:125], s[6:7]
	s_waitcnt lgkmcnt(1)
	v_add_u32_e32 v136, 0xc0000, v132
	global_store_dwordx2 v136, v[126:127], s[6:7]
	s_waitcnt lgkmcnt(0)
	v_add_u32_e32 v136, 0xe0000, v132
	global_store_dwordx2 v136, v[128:129], s[6:7]
	s_barrier
; template <int MODE>
; DI void gemm_tile(const Params& p, const bf16_t* __restrict__ A, const bf16_t* __restrict__ Bt, int K, int brow, int bcol, int mp, int nt, bool vt, char* smem) {
;     ...
;       for (int m = 0; m < 4; ++m)
; #pragma unroll
;         for (int n = 0; n < 2; ++n) *(f32x4*)(st + (wc * 32 + n * 16 + fr) * 132 + wr * 64 + m * 16 + fq * 4) = acc[ai][bj][m][n];
;       __syncthreads();
; #pragma unroll 1
;       for (int pg = 0; pg < 2; ++pg) {
;       u32x2 xo[4];
;       if (RESID) {
; #pragma unroll
;         for (int pq = 0; pq < 4; ++pq) xo[pq] = xnx[pq];
;         const int q = ai * 2 + bj, nq = pg ? q + 1 : q, npg = pg ^ 1;
;         if (nq < 4) {
;           const int nai = nq >> 1, nbj = nq & 1;
; #pragma unroll
;           for (int pq = 0; pq < 4; ++pq)
;             xnx[pq] = *(const u32x2*)((const bf16_t*)(p.ws + OFF_XB) + (size_t)(m0 + nbj * 128 + (npg * 4 + pq) * 16 + (tid >> 5)) * DM + n0 + nai * 128 + (tid & 31) * 4);
;         }
;       }
; #pragma unroll
;       for (int pq = 0; pq < 4; ++pq) {
;         const int pass = pg * 4 + pq;
;         const int y = pass * 16 + (tid >> 5), x4 = (tid & 31) * 4;
;         const f32x4 v = *(const f32x4*)(st + y * 132 + x4);
;         if (MODE == MODE_PROJ) {
;           if (vt) {
;             const int vrow = (nt - 8) * 256 + bj * 128 + y, tk = m0 + ai * 128 + x4, b = tk >> 11, sq = tk & 2047;
;             const f32x4 rr = *(const f32x4*)(rsl + ai * 128 + x4);
;             u32x2 o = {pk2(v[0] * rr[0], v[1] * rr[1]), pk2(v[2] * rr[2], v[3] * rr[3])};
;             *(u32x2*)((bf16_t*)(p.ws + OFF_VT) + ((size_t)(b * VROWS + vrow)) * SEQ + sq) = o;
;           } else {
;             const int tok = m0 + bj * 128 + y, col = n0 + ai * 128 + x4;
;             const float rs = rsl[bj * 128 + y];
;             if (col < QKW) {
;               u32x2 o = {pk2(v[0] * rs, v[1] * rs), pk2(v[2] * rs, v[3] * rs)};
;               *(u32x2*)((bf16_t*)(p.ws + OFF_QK) + (size_t)tok * QKW + col) = o;
;             } else if (col < QKW + 16) {
;               f32x4 o = {v[0] * rs, v[1] * rs, v[2] * rs, v[3] * rs};
;               *(f32x4*)((float*)(p.ws + OFF_GATE) + (size_t)tok * 16 + (col - QKW)) = o;
;             }
;           }
;         } else if (MODE == MODE_UP) {
;           const int tok = m0 + bj * 128 + y, col = n0 + ai * 128 + x4;
;           const float rs = rsl[bj * 128 + y];
	v_mul_f32_e32 v66, v66, v146
	v_mul_f32_e32 v67, v67, v146
	v_mul_f32_e32 v68, v68, v146
	v_mul_f32_e32 v69, v69, v146
	v_max_f32_e32 v66, 0, v66
	v_max_f32_e32 v67, 0, v67
	v_max_f32_e32 v68, 0, v68
	v_max_f32_e32 v69, 0, v69
	v_pk_mul_f32 v[66:67], v[66:67], v[66:67]
	v_pk_mul_f32 v[68:69], v[68:69], v[68:69]
	v_cvt_pk_bf16_f32 v66, v66, v67
	v_cvt_pk_bf16_f32 v67, v68, v69
	ds_write_b64 v134, v[66:67]
	v_mul_f32_e32 v70, v70, v147
	v_mul_f32_e32 v71, v71, v147
	v_mul_f32_e32 v72, v72, v147
	v_mul_f32_e32 v73, v73, v147
	v_max_f32_e32 v70, 0, v70
	v_max_f32_e32 v71, 0, v71
	v_max_f32_e32 v72, 0, v72
	v_max_f32_e32 v73, 0, v73
	v_pk_mul_f32 v[70:71], v[70:71], v[70:71]
	v_pk_mul_f32 v[72:73], v[72:73], v[72:73]
	v_cvt_pk_bf16_f32 v70, v70, v71
	v_cvt_pk_bf16_f32 v71, v72, v73
	ds_write_b64 v134, v[70:71] offset:4224
	v_mul_f32_e32 v74, v74, v146
	v_mul_f32_e32 v75, v75, v146
	v_mul_f32_e32 v76, v76, v146
	v_mul_f32_e32 v77, v77, v146
	v_max_f32_e32 v74, 0, v74
	v_max_f32_e32 v75, 0, v75
	v_max_f32_e32 v76, 0, v76
	v_max_f32_e32 v77, 0, v77
	v_pk_mul_f32 v[74:75], v[74:75], v[74:75]
	v_pk_mul_f32 v[76:77], v[76:77], v[76:77]
	v_cvt_pk_bf16_f32 v74, v74, v75
	v_cvt_pk_bf16_f32 v75, v76, v77
	ds_write_b64 v134, v[74:75] offset:32
	v_mul_f32_e32 v78, v78, v147
	v_mul_f32_e32 v79, v79, v147
	v_mul_f32_e32 v80, v80, v147
	v_mul_f32_e32 v81, v81, v147
	v_max_f32_e32 v78, 0, v78
	v_max_f32_e32 v79, 0, v79
	v_max_f32_e32 v80, 0, v80
	v_max_f32_e32 v81, 0, v81
	v_pk_mul_f32 v[78:79], v[78:79], v[78:79]
	v_pk_mul_f32 v[80:81], v[80:81], v[80:81]
	v_cvt_pk_bf16_f32 v78, v78, v79
	v_cvt_pk_bf16_f32 v79, v80, v81
	ds_write_b64 v134, v[78:79] offset:4256
	v_mul_f32_e32 v82, v82, v146
	v_mul_f32_e32 v83, v83, v146
	v_mul_f32_e32 v84, v84, v146
	v_mul_f32_e32 v85, v85, v146
	v_max_f32_e32 v82, 0, v82
	v_max_f32_e32 v83, 0, v83
	v_max_f32_e32 v84, 0, v84
	v_max_f32_e32 v85, 0, v85
	v_pk_mul_f32 v[82:83], v[82:83], v[82:83]
	v_pk_mul_f32 v[84:85], v[84:85], v[84:85]
	v_cvt_pk_bf16_f32 v82, v82, v83
	v_cvt_pk_bf16_f32 v83, v84, v85
	ds_write_b64 v134, v[82:83] offset:64
	v_mul_f32_e32 v86, v86, v147
	v_mul_f32_e32 v87, v87, v147
	v_mul_f32_e32 v88, v88, v147
	v_mul_f32_e32 v89, v89, v147
	v_max_f32_e32 v86, 0, v86
	v_max_f32_e32 v87, 0, v87
	v_max_f32_e32 v88, 0, v88
	v_max_f32_e32 v89, 0, v89
	v_pk_mul_f32 v[86:87], v[86:87], v[86:87]
	v_pk_mul_f32 v[88:89], v[88:89], v[88:89]
	v_cvt_pk_bf16_f32 v86, v86, v87
	v_cvt_pk_bf16_f32 v87, v88, v89
	ds_write_b64 v134, v[86:87] offset:4288
	v_mul_f32_e32 v90, v90, v146
	v_mul_f32_e32 v91, v91, v146
	v_mul_f32_e32 v92, v92, v146
	v_mul_f32_e32 v93, v93, v146
	v_max_f32_e32 v90, 0, v90
	v_max_f32_e32 v91, 0, v91
	v_max_f32_e32 v92, 0, v92
	v_max_f32_e32 v93, 0, v93
	v_pk_mul_f32 v[90:91], v[90:91], v[90:91]
	v_pk_mul_f32 v[92:93], v[92:93], v[92:93]
	v_cvt_pk_bf16_f32 v90, v90, v91
	v_cvt_pk_bf16_f32 v91, v92, v93
	ds_write_b64 v134, v[90:91] offset:96
	v_mul_f32_e32 v94, v94, v147
	v_mul_f32_e32 v95, v95, v147
	v_mul_f32_e32 v96, v96, v147
	v_mul_f32_e32 v97, v97, v147
	v_max_f32_e32 v94, 0, v94
	v_max_f32_e32 v95, 0, v95
	v_max_f32_e32 v96, 0, v96
	v_max_f32_e32 v97, 0, v97
	v_pk_mul_f32 v[94:95], v[94:95], v[94:95]
	v_pk_mul_f32 v[96:97], v[96:97], v[96:97]
	v_cvt_pk_bf16_f32 v94, v94, v95
	v_cvt_pk_bf16_f32 v95, v96, v97
	ds_write_b64 v134, v[94:95] offset:4320
	s_waitcnt lgkmcnt(0)
	s_barrier
	ds_read_b64 v[82:83], v135
	ds_read_b64 v[84:85], v135 offset:4224
	ds_read_b64 v[86:87], v135 offset:8448
	ds_read_b64 v[88:89], v135 offset:12672
	ds_read_b64 v[90:91], v135 offset:16896
	ds_read_b64 v[92:93], v135 offset:21120
	ds_read_b64 v[94:95], v135 offset:25344
	ds_read_b64 v[96:97], v135 offset:29568
	s_waitcnt lgkmcnt(7)
	v_add_u32_e32 v136, 0x100000, v132
	global_store_dwordx2 v136, v[82:83], s[6:7]
	s_waitcnt lgkmcnt(6)
	v_add_u32_e32 v136, 0x120000, v132
	global_store_dwordx2 v136, v[84:85], s[6:7]
	s_waitcnt lgkmcnt(5)
	v_add_u32_e32 v136, 0x140000, v132
	global_store_dwordx2 v136, v[86:87], s[6:7]
	s_waitcnt lgkmcnt(4)
	v_add_u32_e32 v136, 0x160000, v132
	global_store_dwordx2 v136, v[88:89], s[6:7]
	s_waitcnt lgkmcnt(3)
	v_add_u32_e32 v136, 0x180000, v132
	global_store_dwordx2 v136, v[90:91], s[6:7]
	s_waitcnt lgkmcnt(2)
	v_add_u32_e32 v136, 0x1a0000, v132
	global_store_dwordx2 v136, v[92:93], s[6:7]
	s_waitcnt lgkmcnt(1)
	v_add_u32_e32 v136, 0x1c0000, v132
	global_store_dwordx2 v136, v[94:95], s[6:7]
	s_waitcnt lgkmcnt(0)
	v_add_u32_e32 v136, 0x1e0000, v132
	global_store_dwordx2 v136, v[96:97], s[6:7]
	s_barrier
; template <int MODE>
; DI void gemm_tile(const Params& p, const bf16_t* __restrict__ A, const bf16_t* __restrict__ Bt, int K, int brow, int bcol, int mp, int nt, bool vt, char* smem) {
;     ...
;       for (int m = 0; m < 4; ++m)
; #pragma unroll
;         for (int n = 0; n < 2; ++n) *(f32x4*)(st + (wc * 32 + n * 16 + fr) * 132 + wr * 64 + m * 16 + fq * 4) = acc[ai][bj][m][n];
;       __syncthreads();
; #pragma unroll 1
;       for (int pg = 0; pg < 2; ++pg) {
;       u32x2 xo[4];
;       if (RESID) {
; #pragma unroll
;         for (int pq = 0; pq < 4; ++pq) xo[pq] = xnx[pq];
;         const int q = ai * 2 + bj, nq = pg ? q + 1 : q, npg = pg ^ 1;
;         if (nq < 4) {
;           const int nai = nq >> 1, nbj = nq & 1;
; #pragma unroll
;           for (int pq = 0; pq < 4; ++pq)
;             xnx[pq] = *(const u32x2*)((const bf16_t*)(p.ws + OFF_XB) + (size_t)(m0 + nbj * 128 + (npg * 4 + pq) * 16 + (tid >> 5)) * DM + n0 + nai * 128 + (tid & 31) * 4);
;         }
;       }
; #pragma unroll
;       for (int pq = 0; pq < 4; ++pq) {
;         const int pass = pg * 4 + pq;
;         const int y = pass * 16 + (tid >> 5), x4 = (tid & 31) * 4;
;         const f32x4 v = *(const f32x4*)(st + y * 132 + x4);
;         if (MODE == MODE_PROJ) {
;           if (vt) {
;             const int vrow = (nt - 8) * 256 + bj * 128 + y, tk = m0 + ai * 128 + x4, b = tk >> 11, sq = tk & 2047;
;             const f32x4 rr = *(const f32x4*)(rsl + ai * 128 + x4);
;             u32x2 o = {pk2(v[0] * rr[0], v[1] * rr[1]), pk2(v[2] * rr[2], v[3] * rr[3])};
;             *(u32x2*)((bf16_t*)(p.ws + OFF_VT) + ((size_t)(b * VROWS + vrow)) * SEQ + sq) = o;
;           } else {
;             const int tok = m0 + bj * 128 + y, col = n0 + ai * 128 + x4;
;             const float rs = rsl[bj * 128 + y];
;             if (col < QKW) {
;               u32x2 o = {pk2(v[0] * rs, v[1] * rs), pk2(v[2] * rs, v[3] * rs)};
;               *(u32x2*)((bf16_t*)(p.ws + OFF_QK) + (size_t)tok * QKW + col) = o;
;             } else if (col < QKW + 16) {
;               f32x4 o = {v[0] * rs, v[1] * rs, v[2] * rs, v[3] * rs};
;               *(f32x4*)((float*)(p.ws + OFF_GATE) + (size_t)tok * 16 + (col - QKW)) = o;
;             }
;           }
;         } else if (MODE == MODE_UP) {
;           const int tok = m0 + bj * 128 + y, col = n0 + ai * 128 + x4;
;           const float rs = rsl[bj * 128 + y];
	v_mul_f32_e32 v34, v34, v144
	v_mul_f32_e32 v35, v35, v144
	v_mul_f32_e32 v36, v36, v144
	v_mul_f32_e32 v37, v37, v144
	v_max_f32_e32 v34, 0, v34
	v_max_f32_e32 v35, 0, v35
	v_max_f32_e32 v36, 0, v36
	v_max_f32_e32 v37, 0, v37
	v_pk_mul_f32 v[34:35], v[34:35], v[34:35]
	v_pk_mul_f32 v[36:37], v[36:37], v[36:37]
	v_cvt_pk_bf16_f32 v34, v34, v35
	v_cvt_pk_bf16_f32 v35, v36, v37
	ds_write_b64 v134, v[34:35]
	v_mul_f32_e32 v38, v38, v145
	v_mul_f32_e32 v39, v39, v145
	v_mul_f32_e32 v40, v40, v145
	v_mul_f32_e32 v41, v41, v145
	v_max_f32_e32 v38, 0, v38
	v_max_f32_e32 v39, 0, v39
	v_max_f32_e32 v40, 0, v40
	v_max_f32_e32 v41, 0, v41
	v_pk_mul_f32 v[38:39], v[38:39], v[38:39]
	v_pk_mul_f32 v[40:41], v[40:41], v[40:41]
	v_cvt_pk_bf16_f32 v38, v38, v39
	v_cvt_pk_bf16_f32 v39, v40, v41
	ds_write_b64 v134, v[38:39] offset:4224
	v_mul_f32_e32 v42, v42, v144
	v_mul_f32_e32 v43, v43, v144
	v_mul_f32_e32 v44, v44, v144
	v_mul_f32_e32 v45, v45, v144
	v_max_f32_e32 v42, 0, v42
	v_max_f32_e32 v43, 0, v43
	v_max_f32_e32 v44, 0, v44
	v_max_f32_e32 v45, 0, v45
	v_pk_mul_f32 v[42:43], v[42:43], v[42:43]
	v_pk_mul_f32 v[44:45], v[44:45], v[44:45]
	v_cvt_pk_bf16_f32 v42, v42, v43
	v_cvt_pk_bf16_f32 v43, v44, v45
	ds_write_b64 v134, v[42:43] offset:32
	v_mul_f32_e32 v46, v46, v145
	v_mul_f32_e32 v47, v47, v145
	v_mul_f32_e32 v48, v48, v145
	v_mul_f32_e32 v49, v49, v145
	v_max_f32_e32 v46, 0, v46
	v_max_f32_e32 v47, 0, v47
	v_max_f32_e32 v48, 0, v48
	v_max_f32_e32 v49, 0, v49
	v_pk_mul_f32 v[46:47], v[46:47], v[46:47]
	v_pk_mul_f32 v[48:49], v[48:49], v[48:49]
	v_cvt_pk_bf16_f32 v46, v46, v47
	v_cvt_pk_bf16_f32 v47, v48, v49
	ds_write_b64 v134, v[46:47] offset:4256
	v_mul_f32_e32 v50, v50, v144
	v_mul_f32_e32 v51, v51, v144
	v_mul_f32_e32 v52, v52, v144
	v_mul_f32_e32 v53, v53, v144
	v_max_f32_e32 v50, 0, v50
	v_max_f32_e32 v51, 0, v51
	v_max_f32_e32 v52, 0, v52
	v_max_f32_e32 v53, 0, v53
	v_pk_mul_f32 v[50:51], v[50:51], v[50:51]
	v_pk_mul_f32 v[52:53], v[52:53], v[52:53]
	v_cvt_pk_bf16_f32 v50, v50, v51
	v_cvt_pk_bf16_f32 v51, v52, v53
	ds_write_b64 v134, v[50:51] offset:64
	v_mul_f32_e32 v54, v54, v145
	v_mul_f32_e32 v55, v55, v145
	v_mul_f32_e32 v56, v56, v145
	v_mul_f32_e32 v57, v57, v145
	v_max_f32_e32 v54, 0, v54
	v_max_f32_e32 v55, 0, v55
	v_max_f32_e32 v56, 0, v56
	v_max_f32_e32 v57, 0, v57
	v_pk_mul_f32 v[54:55], v[54:55], v[54:55]
	v_pk_mul_f32 v[56:57], v[56:57], v[56:57]
	v_cvt_pk_bf16_f32 v54, v54, v55
	v_cvt_pk_bf16_f32 v55, v56, v57
	ds_write_b64 v134, v[54:55] offset:4288
	v_mul_f32_e32 v58, v58, v144
	v_mul_f32_e32 v59, v59, v144
	v_mul_f32_e32 v60, v60, v144
	v_mul_f32_e32 v61, v61, v144
	v_max_f32_e32 v58, 0, v58
	v_max_f32_e32 v59, 0, v59
	v_max_f32_e32 v60, 0, v60
	v_max_f32_e32 v61, 0, v61
	v_pk_mul_f32 v[58:59], v[58:59], v[58:59]
	v_pk_mul_f32 v[60:61], v[60:61], v[60:61]
	v_cvt_pk_bf16_f32 v58, v58, v59
	v_cvt_pk_bf16_f32 v59, v60, v61
	ds_write_b64 v134, v[58:59] offset:96
	v_mul_f32_e32 v62, v62, v145
	v_mul_f32_e32 v63, v63, v145
	v_mul_f32_e32 v64, v64, v145
	v_mul_f32_e32 v65, v65, v145
	v_max_f32_e32 v62, 0, v62
	v_max_f32_e32 v63, 0, v63
	v_max_f32_e32 v64, 0, v64
	v_max_f32_e32 v65, 0, v65
	v_pk_mul_f32 v[62:63], v[62:63], v[62:63]
	v_pk_mul_f32 v[64:65], v[64:65], v[64:65]
	v_cvt_pk_bf16_f32 v62, v62, v63
	v_cvt_pk_bf16_f32 v63, v64, v65
	ds_write_b64 v134, v[62:63] offset:4320
	s_waitcnt lgkmcnt(0)
	s_barrier
	ds_read_b64 v[50:51], v135
	ds_read_b64 v[52:53], v135 offset:4224
	ds_read_b64 v[54:55], v135 offset:8448
	ds_read_b64 v[56:57], v135 offset:12672
	ds_read_b64 v[58:59], v135 offset:16896
	ds_read_b64 v[60:61], v135 offset:21120
	ds_read_b64 v[62:63], v135 offset:25344
	ds_read_b64 v[64:65], v135 offset:29568
	s_waitcnt lgkmcnt(7)
	global_store_dwordx2 v132, v[50:51], s[6:7] offset:256
	s_waitcnt lgkmcnt(6)
	v_add_u32_e32 v136, 0x20000, v132
	global_store_dwordx2 v136, v[52:53], s[6:7] offset:256
	s_waitcnt lgkmcnt(5)
	v_add_u32_e32 v136, 0x40000, v132
	global_store_dwordx2 v136, v[54:55], s[6:7] offset:256
	s_waitcnt lgkmcnt(4)
	v_add_u32_e32 v136, 0x60000, v132
	global_store_dwordx2 v136, v[56:57], s[6:7] offset:256
	s_waitcnt lgkmcnt(3)
	v_add_u32_e32 v136, 0x80000, v132
	global_store_dwordx2 v136, v[58:59], s[6:7] offset:256
	s_waitcnt lgkmcnt(2)
	v_add_u32_e32 v136, 0xa0000, v132
	global_store_dwordx2 v136, v[60:61], s[6:7] offset:256
	s_waitcnt lgkmcnt(1)
	v_add_u32_e32 v136, 0xc0000, v132
	global_store_dwordx2 v136, v[62:63], s[6:7] offset:256
	s_waitcnt lgkmcnt(0)
	v_add_u32_e32 v136, 0xe0000, v132
	global_store_dwordx2 v136, v[64:65], s[6:7] offset:256
	s_barrier
; DI unsigned pk2(float a, float b) { f32x2 v = {a, b}; bf2_t r = __builtin_convertvector(v, bf2_t); return __builtin_bit_cast(unsigned, r); }
; DI f32x4 unpk4(u32x2 u) { f32x4 r = {__uint_as_float(u[0] << 16), __uint_as_float(u[0] & 0xffff0000u), __uint_as_float(u[1] << 16), __uint_as_float(u[1] & 0xffff0000u)}; return r; }
; template <int MODE>
; DI void gemm_tile(const Params& p, const bf16_t* __restrict__ A, const bf16_t* __restrict__ Bt, int K, int brow, int bcol, int mp, int nt, bool vt, char* smem) {
;     ...
;         } else if (MODE == MODE_UP) {
;           const int tok = m0 + bj * 128 + y, col = n0 + ai * 128 + x4;
;           const float rs = rsl[bj * 128 + y];
;           const float a0 = fmaxf(v[0] * rs, 0.f), a1 = fmaxf(v[1] * rs, 0.f), a2 = fmaxf(v[2] * rs, 0.f), a3 = fmaxf(v[3] * rs, 0.f);
;           u32x2 o = {pk2(a0 * a0, a1 * a1), pk2(a2 * a2, a3 * a3)};
;           *(u32x2*)((bf16_t*)(p.ws + OFF_U) + (size_t)tok * DFF + col) = o;
;         } else {
;           const int tok = m0 + bj * 128 + y, col = n0 + ai * 128 + x4;
;           const f32x4 xs = unpk4(xo[pq]) + v;
;           u32x2 o = {pk2(xs[0], xs[1]), pk2(xs[2], xs[3])};
;           *(u32x2*)((bf16_t*)(p.ws + OFF_XB) + (size_t)tok * DM + col) = o;
;           const f32x4 xn = unpk4(o);
;           float ss = xn[0] * xn[0] + xn[1] * xn[1] + xn[2] * xn[2] + xn[3] * xn[3];
; #pragma unroll
;           for (int o2 = 16; o2 > 0; o2 >>= 1) ss += __shfl_xor(ss, o2);
;           if ((tid & 31) == 0) ((float*)(p.ws + (MODE == MODE_OUT ? OFF_SSB : OFF_SSA)))[(size_t)tok * 8 + nt * 2 + ai] = ss;
;         }
;       }
;       }
;       __syncthreads();
; template <int MODE>
; DI void phase_gemm(const Params& p, int l, char* smem) {
;     ...
;   for (int L = xmap ? (int)(blockIdx.x >> 3) : (int)blockIdx.x; L < tot; L += nb) {
	v_mul_f32_e32 v2, v2, v146
	v_mul_f32_e32 v3, v3, v146
	v_mul_f32_e32 v4, v4, v146
	v_mul_f32_e32 v5, v5, v146
	v_max_f32_e32 v2, 0, v2
	v_max_f32_e32 v3, 0, v3
	v_max_f32_e32 v4, 0, v4
	v_max_f32_e32 v5, 0, v5
	v_pk_mul_f32 v[2:3], v[2:3], v[2:3]
	v_pk_mul_f32 v[4:5], v[4:5], v[4:5]
	v_cvt_pk_bf16_f32 v2, v2, v3
	v_cvt_pk_bf16_f32 v3, v4, v5
	ds_write_b64 v134, v[2:3]
	v_mul_f32_e32 v6, v6, v147
	v_mul_f32_e32 v7, v7, v147
	v_mul_f32_e32 v8, v8, v147
	v_mul_f32_e32 v9, v9, v147
	v_max_f32_e32 v6, 0, v6
	v_max_f32_e32 v7, 0, v7
	v_max_f32_e32 v8, 0, v8
	v_max_f32_e32 v9, 0, v9
	v_pk_mul_f32 v[6:7], v[6:7], v[6:7]
	v_pk_mul_f32 v[8:9], v[8:9], v[8:9]
	v_cvt_pk_bf16_f32 v6, v6, v7
	v_cvt_pk_bf16_f32 v7, v8, v9
	ds_write_b64 v134, v[6:7] offset:4224
	v_mul_f32_e32 v10, v10, v146
	v_mul_f32_e32 v11, v11, v146
	v_mul_f32_e32 v12, v12, v146
	v_mul_f32_e32 v13, v13, v146
	v_max_f32_e32 v10, 0, v10
	v_max_f32_e32 v11, 0, v11
	v_max_f32_e32 v12, 0, v12
	v_max_f32_e32 v13, 0, v13
	v_pk_mul_f32 v[10:11], v[10:11], v[10:11]
	v_pk_mul_f32 v[12:13], v[12:13], v[12:13]
	v_cvt_pk_bf16_f32 v10, v10, v11
	v_cvt_pk_bf16_f32 v11, v12, v13
	ds_write_b64 v134, v[10:11] offset:32
	v_mul_f32_e32 v14, v14, v147
	v_mul_f32_e32 v15, v15, v147
	v_mul_f32_e32 v16, v16, v147
	v_mul_f32_e32 v17, v17, v147
	v_max_f32_e32 v14, 0, v14
	v_max_f32_e32 v15, 0, v15
	v_max_f32_e32 v16, 0, v16
	v_max_f32_e32 v17, 0, v17
	v_pk_mul_f32 v[14:15], v[14:15], v[14:15]
	v_pk_mul_f32 v[16:17], v[16:17], v[16:17]
	v_cvt_pk_bf16_f32 v14, v14, v15
	v_cvt_pk_bf16_f32 v15, v16, v17
	ds_write_b64 v134, v[14:15] offset:4256
	v_mul_f32_e32 v18, v18, v146
	v_mul_f32_e32 v19, v19, v146
	v_mul_f32_e32 v20, v20, v146
	v_mul_f32_e32 v21, v21, v146
	v_max_f32_e32 v18, 0, v18
	v_max_f32_e32 v19, 0, v19
	v_max_f32_e32 v20, 0, v20
	v_max_f32_e32 v21, 0, v21
	v_pk_mul_f32 v[18:19], v[18:19], v[18:19]
	v_pk_mul_f32 v[20:21], v[20:21], v[20:21]
	v_cvt_pk_bf16_f32 v18, v18, v19
	v_cvt_pk_bf16_f32 v19, v20, v21
	ds_write_b64 v134, v[18:19] offset:64
	v_mul_f32_e32 v22, v22, v147
	v_mul_f32_e32 v23, v23, v147
	v_mul_f32_e32 v24, v24, v147
	v_mul_f32_e32 v25, v25, v147
	v_max_f32_e32 v22, 0, v22
	v_max_f32_e32 v23, 0, v23
	v_max_f32_e32 v24, 0, v24
	v_max_f32_e32 v25, 0, v25
	v_pk_mul_f32 v[22:23], v[22:23], v[22:23]
	v_pk_mul_f32 v[24:25], v[24:25], v[24:25]
	v_cvt_pk_bf16_f32 v22, v22, v23
	v_cvt_pk_bf16_f32 v23, v24, v25
	ds_write_b64 v134, v[22:23] offset:4288
	v_mul_f32_e32 v26, v26, v146
	v_mul_f32_e32 v27, v27, v146
	v_mul_f32_e32 v28, v28, v146
	v_mul_f32_e32 v29, v29, v146
	v_max_f32_e32 v26, 0, v26
	v_max_f32_e32 v27, 0, v27
	v_max_f32_e32 v28, 0, v28
	v_max_f32_e32 v29, 0, v29
	v_pk_mul_f32 v[26:27], v[26:27], v[26:27]
	v_pk_mul_f32 v[28:29], v[28:29], v[28:29]
	v_cvt_pk_bf16_f32 v26, v26, v27
	v_cvt_pk_bf16_f32 v27, v28, v29
	ds_write_b64 v134, v[26:27] offset:96
	v_mul_f32_e32 v30, v30, v147
	v_mul_f32_e32 v31, v31, v147
	v_mul_f32_e32 v32, v32, v147
	v_mul_f32_e32 v33, v33, v147
	v_max_f32_e32 v30, 0, v30
	v_max_f32_e32 v31, 0, v31
	v_max_f32_e32 v32, 0, v32
	v_max_f32_e32 v33, 0, v33
	v_pk_mul_f32 v[30:31], v[30:31], v[30:31]
	v_pk_mul_f32 v[32:33], v[32:33], v[32:33]
	v_cvt_pk_bf16_f32 v30, v30, v31
	v_cvt_pk_bf16_f32 v31, v32, v33
	ds_write_b64 v134, v[30:31] offset:4320
	s_waitcnt lgkmcnt(0)
	s_barrier
	ds_read_b64 v[18:19], v135
	ds_read_b64 v[20:21], v135 offset:4224
	ds_read_b64 v[22:23], v135 offset:8448
	ds_read_b64 v[24:25], v135 offset:12672
	ds_read_b64 v[26:27], v135 offset:16896
	ds_read_b64 v[28:29], v135 offset:21120
	ds_read_b64 v[30:31], v135 offset:25344
	ds_read_b64 v[32:33], v135 offset:29568
	s_waitcnt lgkmcnt(7)
	v_add_u32_e32 v136, 0x100000, v132
	global_store_dwordx2 v136, v[18:19], s[6:7] offset:256
	s_waitcnt lgkmcnt(6)
	v_add_u32_e32 v136, 0x120000, v132
	global_store_dwordx2 v136, v[20:21], s[6:7] offset:256
	s_waitcnt lgkmcnt(5)
	v_add_u32_e32 v136, 0x140000, v132
	global_store_dwordx2 v136, v[22:23], s[6:7] offset:256
	s_waitcnt lgkmcnt(4)
	v_add_u32_e32 v136, 0x160000, v132
	global_store_dwordx2 v136, v[24:25], s[6:7] offset:256
	s_waitcnt lgkmcnt(3)
	v_add_u32_e32 v136, 0x180000, v132
	global_store_dwordx2 v136, v[26:27], s[6:7] offset:256
	s_waitcnt lgkmcnt(2)
	v_add_u32_e32 v136, 0x1a0000, v132
	global_store_dwordx2 v136, v[28:29], s[6:7] offset:256
	s_waitcnt lgkmcnt(1)
	v_add_u32_e32 v136, 0x1c0000, v132
	global_store_dwordx2 v136, v[30:31], s[6:7] offset:256
	s_waitcnt lgkmcnt(0)
	v_add_u32_e32 v136, 0x1e0000, v132
	global_store_dwordx2 v136, v[32:33], s[6:7] offset:256
	s_add_i32 s22, s22, s60
	v_readlane_b32 s0, v246, 4
	s_cmp_ge_i32 s22, s0
	s_nop 0
	s_cbranch_scc0 .LBB0_29
